# combo2 plus w_in N-tile rotation pn=(pn+(pm>>2))&7: each workgroup cycles through all 8 N-tiles, balancing the expensive head epilogues
# speedup vs baseline: 1.0050x; 1.0012x over previous
.LBB0_224:
	s_or_b64 exec, exec, s[2:3]
	v_readlane_b32 s0, v254, 29
	v_mov_b32_e32 v9, v234
	v_readlane_b32 s1, v254, 30
	s_waitcnt lgkmcnt(0)
	s_barrier
	s_andn2_b64 vcc, exec, s[0:1]
	v_readfirstlane_b32 s0, v9
	v_readlane_b32 s40, v254, 23
	v_readlane_b32 s72, v254, 24
	v_readlane_b32 s73, v254, 25
	v_readlane_b32 s74, v254, 26
	s_cbranch_vccnz .LBB0_336
	v_lshlrev_b32_e32 v0, 4, v9
	v_add_u32_e32 v2, 0x2000, v0
	v_ashrrev_i32_e32 v3, 31, v2
	v_lshrrev_b32_e32 v3, 22, v3
	v_add_u32_e32 v3, v2, v3
	v_ashrrev_i32_e32 v6, 10, v3
	v_mul_i32_i24_e32 v4, 0x400, v6
	v_sub_u32_e32 v2, v2, v4
	v_lshrrev_b32_e32 v4, 4, v2
	v_bitop3_b32 v2, v4, v2, 32 bitop3:0x6c
	v_ashrrev_i32_e32 v4, 31, v2
	v_lshrrev_b32_e32 v4, 26, v4
	v_add_u32_e32 v4, v2, v4
	v_ashrrev_i32_e32 v7, 6, v4
	v_and_b32_e32 v4, 0xc0, v4
	v_sub_u32_e32 v2, v2, v4
	v_mov_b32_e32 v4, 1
	v_lshlrev_b32_e32 v3, 5, v6
	v_ashrrev_i16_sdwa v2, v4, sext(v2) dst_sel:DWORD dst_unused:UNUSED_PAD src0_sel:DWORD src1_sel:BYTE_0
	v_and_b32_e32 v3, 32, v3
	v_bfe_i32 v8, v2, 0, 16
	v_add_u32_e32 v2, v3, v8
	v_lshlrev_b32_e32 v3, 3, v6
	v_and_b32_e32 v3, 0x1ffff0, v3
	v_add_lshl_u32 v3, v7, v3, 11
	v_lshl_add_u32 v170, v2, 1, v3
	v_bfe_i32 v3, v9, 27, 1
	v_lshrrev_b32_e32 v3, 22, v3
	v_add_u32_e32 v3, v0, v3
	v_and_b32_e32 v3, 0xfffffc00, v3
	v_sub_u32_e32 v0, v0, v3
	v_lshrrev_b32_e32 v3, 4, v0
	v_bitop3_b32 v3, v3, v0, 32 bitop3:0x6c
	v_ashrrev_i32_e32 v0, 31, v0
	v_lshrrev_b32_e32 v0, 26, v0
	v_ashrrev_i32_e32 v2, 31, v9
	v_add_u32_e32 v0, v3, v0
	v_lshrrev_b32_e32 v2, 26, v2
	v_ashrrev_i32_e32 v11, 6, v0
	v_add_u32_e32 v2, v9, v2
	v_mul_i32_i24_e32 v0, 64, v11
	v_ashrrev_i32_e32 v10, 6, v2
	v_sub_u32_e32 v0, v3, v0
	s_add_u32 s52, s97, 0x2100000
	v_lshlrev_b32_e32 v2, 5, v10
	v_ashrrev_i16_sdwa v0, v4, sext(v0) dst_sel:DWORD dst_unused:UNUSED_PAD src0_sel:DWORD src1_sel:BYTE_0
	s_addc_u32 s53, s30, 0
	s_ashr_i32 s2, s0, 6
	v_and_b32_e32 v2, 32, v2
	v_bfe_i32 v12, v0, 0, 16
	s_ashr_i32 s1, s0, 8
	s_lshl_b32 s64, s2, 10
	v_add_u32_e32 v0, v2, v12
	v_lshlrev_b32_e32 v2, 3, v10
	v_readlane_b32 s4, v255, 5
	v_and_b32_e32 v2, 0x1ffff0, v2
	v_readlane_b32 s5, v255, 8
	v_add_lshl_u32 v2, v11, v2, 11
	s_nop 3
	s_lshr_b32 s5, s5, 2
	s_add_i32 s4, s4, s5
	s_and_b32 s4, s4, 7
	s_mov_b32 s99, s4
	s_lshl_b32 s4, s4, 19
	s_add_u32 s4, s52, s4
	s_addc_u32 s5, s53, 0
	s_add_i32 s65, s64, 0
	v_lshl_add_u32 v172, v0, 1, v2
	s_add_i32 m0, s65, 0x10000
	v_mov_b32_e32 v173, v1
	global_load_lds_dwordx4 v172, s[4:5]
	s_add_i32 m0, s65, 0x12000
	s_add_u32 s6, s4, 0x40000
	global_load_lds_dwordx4 v170, s[4:5]
	s_addc_u32 s7, s5, 0
	s_add_i32 m0, s65, 0x14000
	s_add_i32 s68, s65, 0x2000
	global_load_lds_dwordx4 v172, s[6:7]
	s_add_i32 m0, s65, 0x16000
	s_add_i32 s69, s65, 0x4000
	global_load_lds_dwordx4 v170, s[6:7]
	v_readlane_b32 s6, v255, 10
	s_mov_b32 m0, s65
	v_readlane_b32 s7, v255, 11
	s_add_i32 s70, s65, 0x6000
	v_mov_b32_e32 v171, v1
	s_cmp_eq_u32 s1, 1
	s_mov_b32 s35, s30
	v_lshl_add_u64 v[2:3], s[4:5], 0, v[172:173]
	global_load_lds_dwordx4 v172, s[6:7]
	s_mov_b32 m0, s68
	s_cselect_b64 s[76:77], -1, 0
	global_load_lds_dwordx4 v170, s[6:7]
	v_readlane_b32 s6, v255, 12
	s_mov_b32 m0, s69
	v_readlane_b32 s7, v255, 13
	s_cmp_lg_u32 s1, 1
	v_lshl_add_u64 v[4:5], s[4:5], 0, v[170:171]
	s_nop 2
	global_load_lds_dwordx4 v172, s[6:7]
	s_mov_b32 m0, s70
	s_nop 0
	global_load_lds_dwordx4 v170, s[6:7]
	s_cbranch_scc1 .LBB0_227
	s_barrier
.LBB0_227:
	v_readlane_b32 s8, v255, 10
	v_readlane_b32 s9, v255, 11
	s_and_b32 s6, s2, 3
	s_add_i32 m0, s65, 0x18000
	v_lshl_add_u64 v[2:3], v[2:3], 0, s[22:23]
	v_lshl_add_u64 v[14:15], s[8:9], 0, v[172:173]
	s_lshl_b32 s71, s1, 6
	s_lshl_b32 s1, s1, 13
	s_lshl_b32 s7, s6, 12
	s_waitcnt vmcnt(2)
	s_barrier
	global_load_lds_dwordx4 v[2:3], off
	v_lshl_add_u64 v[2:3], v[4:5], 0, s[22:23]
	s_add_i32 m0, s65, 0x1a000
	s_add_i32 s94, s65, 0x8000
	s_add_i32 s95, s65, 0xa000
	v_lshl_add_u64 v[16:17], s[8:9], 0, v[170:171]
	global_load_lds_dwordx4 v[2:3], off
	v_lshl_add_u64 v[2:3], v[14:15], 0, s[22:23]
	s_mov_b32 m0, s94
	s_add_u32 s2, s4, 0x40080
	global_load_lds_dwordx4 v[2:3], off
	v_lshl_add_u64 v[2:3], v[16:17], 0, s[22:23]
	s_mov_b32 m0, s95
	s_addc_u32 s3, s5, 0
	global_load_lds_dwordx4 v[2:3], off
	s_add_i32 m0, s65, 0x1c000
	v_lshl_add_u64 v[2:3], s[2:3], 0, v[172:173]
	global_load_lds_dwordx4 v[2:3], off
	v_lshl_add_u64 v[2:3], s[2:3], 0, v[170:171]
	s_add_i32 m0, s65, 0x1e000
	v_and_b32_e32 v175, 15, v9
	global_load_lds_dwordx4 v[2:3], off
	v_bfe_u32 v2, v9, 4, 2
	s_cmpk_lt_u32 s0, 0x100
	v_lshlrev_b32_e32 v0, 4, v2
	v_lshlrev_b32_e32 v3, 6, v175
	v_lshlrev_b32_e32 v5, 2, v9
	s_cselect_b64 s[78:79], -1, 0
	s_cmp_gt_u32 s6, 1
	v_or_b32_e32 v4, v3, v0
	v_and_b32_e32 v5, 32, v5
	s_cselect_b64 s[80:81], -1, 0
	s_bfe_u32 s51, s0, 0x10006
	v_readlane_b32 s0, v255, 28
	v_bitop3_b32 v9, v4, s1, v5 bitop3:0xde
	s_lshl_b32 s50, s6, 6
	v_add_u32_e32 v195, s0, v0
	v_readlane_b32 s0, v254, 27
	v_readlane_b32 s1, v254, 28
	s_add_u32 s0, s0, s50
	s_addc_u32 s1, s1, 0
	v_lshl_add_u64 v[176:177], s[0:1], 0, v[0:1]
	v_readlane_b32 s0, v255, 26
	v_lshlrev_b32_e32 v190, 3, v2
	v_lshlrev_b32_e32 v174, 2, v2
	v_add_u32_e32 v196, s0, v0
	v_readlane_b32 s0, v255, 29
	v_lshlrev_b32_e32 v192, 9, v2
	v_and_b32_e32 v2, 1, v10
	v_add_u32_e32 v197, s0, v0
	v_lshlrev_b32_e32 v0, 14, v10
	v_and_b32_e32 v0, 0xffff8000, v0
	v_lshl_add_u32 v0, v11, 11, v0
	v_lshl_or_b32 v0, v2, 6, v0
	v_lshl_add_u32 v178, v12, 1, v0
	v_lshlrev_b32_e32 v0, 14, v6
	s_and_b64 s[0:1], s[80:81], exec
	v_and_b32_e32 v0, 0xffff8000, v0
	s_waitcnt vmcnt(6)
	v_lshl_add_u32 v0, v7, 11, v0
	v_and_b32_e32 v2, 1, v6
	v_readlane_b32 s0, v255, 8
	v_lshl_or_b32 v0, v2, 6, v0
	v_readlane_b32 s1, v255, 9
	v_bitop3_b32 v191, v4, s7, v5 bitop3:0xde
	v_or_b32_e32 v193, 32, v190
	v_or_b32_e32 v194, 0x800, v192
	v_add_u32_e32 v198, v196, v3
	v_add_u32_e32 v199, v197, v3
	s_cselect_b32 s75, s74, s72
	s_cselect_b32 s74, s73, s40
	v_mov_b32_e32 v179, v1
	v_lshl_add_u32 v180, v8, 1, v0
	v_mov_b32_e32 v181, v1
	s_mov_b32 s46, 0
	v_add_u32_e32 v200, 0, v9
	s_mov_b32 s47, s99
	s_mov_b32 s10, s0
	s_mov_b64 s[0:1], s[8:9]
	s_movk_i32 s28, 0x109
	s_movk_i32 s29, 0x84
	s_mov_b32 s34, 0x3e38aa3b
	s_mov_b64 s[38:39], 0x10000
	s_barrier
	s_branch .LBB0_230

.LBB0_232:
	s_lshr_b32 s3, s2, 2
	s_add_i32 s16, s16, s3
	s_and_b32 s16, s16, 7
	s_ashr_i32 s3, s2, 31
	s_lshl_b64 s[8:9], s[2:3], 19
	s_add_u32 s44, s48, s8
	s_addc_u32 s45, s49, s9
	s_and_b64 s[8:9], s[6:7], exec
	s_cselect_b32 s3, s45, s1
	s_cselect_b32 s11, s44, s0
	s_ashr_i32 s17, s16, 31
	s_lshl_b64 s[8:9], s[16:17], 19
	s_add_u32 s30, s52, s8
	s_addc_u32 s31, s53, s9
	s_and_b64 s[8:9], s[6:7], exec
	s_cselect_b32 s12, s31, s5
	s_cselect_b32 s13, s30, s4
	s_add_u32 s0, s0, 0x40080
	s_addc_u32 s1, s1, 0
	s_add_u32 s14, s4, 0x100
	v_mov_b32_e32 v18, 0
	s_addc_u32 s15, s5, 0
	s_mov_b32 s17, -2
	v_mov_b32_e32 v19, v18
	v_mov_b32_e32 v20, v18
	v_mov_b32_e32 v21, v18
	v_mov_b32_e32 v22, v18
	v_mov_b32_e32 v23, v18
	v_mov_b32_e32 v24, v18
	v_mov_b32_e32 v25, v18
	v_mov_b32_e32 v26, v18
	v_mov_b32_e32 v27, v18
	v_mov_b32_e32 v28, v18
	v_mov_b32_e32 v29, v18
	v_mov_b32_e32 v34, v18
	v_mov_b32_e32 v35, v18
	v_mov_b32_e32 v36, v18
	v_mov_b32_e32 v37, v18
	v_mov_b32_e32 v42, v18
	v_mov_b32_e32 v43, v18
	v_mov_b32_e32 v44, v18
	v_mov_b32_e32 v45, v18
	v_mov_b32_e32 v50, v18
	v_mov_b32_e32 v51, v18
	v_mov_b32_e32 v52, v18
	v_mov_b32_e32 v53, v18
	v_mov_b32_e32 v58, v18
	v_mov_b32_e32 v59, v18
	v_mov_b32_e32 v60, v18
	v_mov_b32_e32 v61, v18
	v_mov_b32_e32 v66, v18
	v_mov_b32_e32 v67, v18
	v_mov_b32_e32 v68, v18
	v_mov_b32_e32 v69, v18
	v_mov_b32_e32 v30, v18
	v_mov_b32_e32 v31, v18
	v_mov_b32_e32 v32, v18
	v_mov_b32_e32 v33, v18
	v_mov_b32_e32 v38, v18
	v_mov_b32_e32 v39, v18
	v_mov_b32_e32 v40, v18
	v_mov_b32_e32 v41, v18
	v_mov_b32_e32 v46, v18
	v_mov_b32_e32 v47, v18
	v_mov_b32_e32 v48, v18
	v_mov_b32_e32 v49, v18
	v_mov_b32_e32 v54, v18
	v_mov_b32_e32 v55, v18
	v_mov_b32_e32 v56, v18
	v_mov_b32_e32 v57, v18
	v_mov_b32_e32 v62, v18
	v_mov_b32_e32 v63, v18
	v_mov_b32_e32 v64, v18
	v_mov_b32_e32 v65, v18
	v_mov_b32_e32 v70, v18
	v_mov_b32_e32 v71, v18
	v_mov_b32_e32 v72, v18
	v_mov_b32_e32 v73, v18
	v_mov_b32_e32 v74, v18
	v_mov_b32_e32 v75, v18
	v_mov_b32_e32 v76, v18
	v_mov_b32_e32 v77, v18
	v_mov_b32_e32 v78, v18
	v_mov_b32_e32 v79, v18
	v_mov_b32_e32 v80, v18
	v_mov_b32_e32 v81, v18
	v_mov_b32_e32 v82, v18
	v_mov_b32_e32 v83, v18
	v_mov_b32_e32 v84, v18
	v_mov_b32_e32 v85, v18
	v_mov_b32_e32 v86, v18
	v_mov_b32_e32 v87, v18
	v_mov_b32_e32 v88, v18
	v_mov_b32_e32 v89, v18
	v_mov_b32_e32 v90, v18
	v_mov_b32_e32 v91, v18
	v_mov_b32_e32 v92, v18
	v_mov_b32_e32 v93, v18
	v_mov_b32_e32 v98, v18
	v_mov_b32_e32 v99, v18
	v_mov_b32_e32 v100, v18
	v_mov_b32_e32 v101, v18
	v_mov_b32_e32 v106, v18
	v_mov_b32_e32 v107, v18
	v_mov_b32_e32 v108, v18
	v_mov_b32_e32 v109, v18
	v_mov_b32_e32 v114, v18
	v_mov_b32_e32 v115, v18
	v_mov_b32_e32 v116, v18
	v_mov_b32_e32 v117, v18
	v_mov_b32_e32 v122, v18
	v_mov_b32_e32 v123, v18
	v_mov_b32_e32 v124, v18
	v_mov_b32_e32 v125, v18
	v_mov_b32_e32 v130, v18
	v_mov_b32_e32 v131, v18
	v_mov_b32_e32 v132, v18
	v_mov_b32_e32 v133, v18
	v_mov_b32_e32 v94, v18
	v_mov_b32_e32 v95, v18
	v_mov_b32_e32 v96, v18
	v_mov_b32_e32 v97, v18
	v_mov_b32_e32 v102, v18
	v_mov_b32_e32 v103, v18
	v_mov_b32_e32 v104, v18
	v_mov_b32_e32 v105, v18
	v_mov_b32_e32 v110, v18
	v_mov_b32_e32 v111, v18
	v_mov_b32_e32 v112, v18
	v_mov_b32_e32 v113, v18
	v_mov_b32_e32 v118, v18
	v_mov_b32_e32 v119, v18
	v_mov_b32_e32 v120, v18
	v_mov_b32_e32 v121, v18
	v_mov_b32_e32 v126, v18
	v_mov_b32_e32 v127, v18
	v_mov_b32_e32 v128, v18
	v_mov_b32_e32 v129, v18
	v_mov_b32_e32 v134, v18
	v_mov_b32_e32 v135, v18
	v_mov_b32_e32 v136, v18
	v_mov_b32_e32 v137, v18
	v_mov_b32_e32 v138, v18
	v_mov_b32_e32 v139, v18
	v_mov_b32_e32 v140, v18
	v_mov_b32_e32 v141, v18
	v_mov_b32_e32 v142, v18
	v_mov_b32_e32 v143, v18
	v_mov_b32_e32 v144, v18
	v_mov_b32_e32 v145, v18
